# LDS fragment reads hoisted one MFMA slot earlier with counted lgkmcnt waits in A and C-FIXREF attention loops (on top of A-loop SGPR-base DMA)
# baseline (speedup 1.0000x reference)
.LBB0_541:
	v_lshl_add_u64 v[164:165], v[160:161], 0, v[172:173]
	s_add_i32 s10, s0, 0xf000
	v_lshl_add_u64 v[96:97], v[164:165], 0, s[12:13]
	s_mov_b32 m0, s10
	v_lshl_add_u64 v[166:167], v[158:159], 0, v[172:173]
	global_load_lds_dwordx4 v[96:97], off
	v_lshl_add_u64 v[96:97], v[166:167], 0, s[14:15]
	s_mov_b32 m0, s8
	s_nop 0
	global_load_lds_dwordx4 v[96:97], off
	ds_read_b128 v[96:99], v201 offset:20480
	ds_read_b128 v[144:147], v201 offset:24576
	ds_read_b128 v[100:103], v202 offset:20480
	ds_read_b128 v[168:171], v202 offset:24576
	v_exp_f32_e32 v180, v80
	v_exp_f32_e32 v181, v81
	v_exp_f32_e32 v182, v82
	v_exp_f32_e32 v183, v83
	ds_read_b128 v[80:83], v204 offset:20480
	ds_read_b128 v[174:177], v204 offset:24576
	s_waitcnt lgkmcnt(5)
	v_mfma_f32_32x32x16_bf16 v[112:127], v[96:99], v[132:135], v[48:63]
	v_exp_f32_e32 v84, v84
	v_exp_f32_e32 v85, v85
	v_exp_f32_e32 v86, v86
	v_exp_f32_e32 v87, v87
	s_waitcnt lgkmcnt(3)
	v_mfma_f32_32x32x16_bf16 v[112:127], v[100:103], v[128:131], v[112:127]
	v_cvt_pk_bf16_f32 v180, v180, v181
	v_cvt_pk_bf16_f32 v181, v182, v183
	v_cvt_pk_bf16_f32 v182, v84, v85
	v_cvt_pk_bf16_f32 v183, v86, v87
	ds_read_b128 v[84:87], v203 offset:20480
	v_mfma_f32_32x32x16_bf16 v[96:111], v[144:147], v[132:135], v[48:63]
	ds_read_b128 v[144:147], v203 offset:24576
	s_waitcnt lgkmcnt(3)
	v_mfma_f32_32x32x16_bf16 v[112:127], v[80:83], v[140:143], v[112:127]
	v_exp_f32_e32 v80, v88
	v_exp_f32_e32 v81, v89
	v_exp_f32_e32 v82, v90
	v_exp_f32_e32 v83, v91
	s_waitcnt lgkmcnt(1)
	v_mfma_f32_32x32x16_bf16 v[112:127], v[84:87], v[136:139], v[112:127]
	v_exp_f32_e32 v84, v92
	v_exp_f32_e32 v85, v93
	v_exp_f32_e32 v86, v94
	v_exp_f32_e32 v87, v95
	v_mfma_f32_32x32x16_bf16 v[96:111], v[168:171], v[128:131], v[96:111]
	v_cvt_pk_bf16_f32 v168, v80, v81
	v_cvt_pk_bf16_f32 v169, v82, v83
	ds_read_b128 v[80:83], v206 offset:8192
	v_cvt_pk_bf16_f32 v170, v84, v85
	v_cvt_pk_bf16_f32 v171, v86, v87
	ds_read_b128 v[84:87], v206 offset:12288
	v_mfma_f32_32x32x16_bf16 v[96:111], v[174:177], v[140:143], v[96:111]
	ds_read_b128 v[88:91], v205 offset:8192
	ds_read_b128 v[92:95], v205 offset:12288
	s_waitcnt lgkmcnt(2)
	v_mfma_f32_32x32x16_bf16 v[0:15], v[84:87], v[180:183], v[0:15]
	v_exp_f32_e32 v217, v64
	v_exp_f32_e32 v218, v65
	v_exp_f32_e32 v219, v66
	v_exp_f32_e32 v216, v67
	v_exp_f32_e32 v221, v68
	v_exp_f32_e32 v222, v69
	v_mfma_f32_32x32x16_bf16 v[16:31], v[80:83], v[180:183], v[16:31]
	v_exp_f32_e32 v223, v70
	v_exp_f32_e32 v220, v71
	ds_read_b128 v[68:71], v200 offset:8192
	ds_read_b128 v[174:177], v200 offset:12288
	v_cvt_pk_bf16_f32 v64, v217, v218
	v_cvt_pk_bf16_f32 v65, v219, v216
	v_cvt_pk_bf16_f32 v66, v221, v222
	v_cvt_pk_bf16_f32 v67, v223, v220
	s_waitcnt lgkmcnt(2)
	v_mfma_f32_32x32x16_bf16 v[0:15], v[92:95], v[168:171], v[0:15]
	v_exp_f32_e32 v225, v72
	v_exp_f32_e32 v226, v73
	v_exp_f32_e32 v227, v74
	v_exp_f32_e32 v224, v75
	v_exp_f32_e32 v229, v76
	v_exp_f32_e32 v230, v77
	v_mfma_f32_32x32x16_bf16 v[16:31], v[88:91], v[168:171], v[16:31]
	v_exp_f32_e32 v231, v78
	v_exp_f32_e32 v228, v79
	v_cvt_pk_bf16_f32 v72, v225, v226
	v_cvt_pk_bf16_f32 v73, v227, v224
	v_cvt_pk_bf16_f32 v74, v229, v230
	v_cvt_pk_bf16_f32 v75, v231, v228
	v_mfma_f32_32x32x16_bf16 v[96:111], v[144:147], v[136:139], v[96:111]
	ds_read_b128 v[76:79], v151 offset:8192
	ds_read_b128 v[184:187], v151 offset:12288
	s_waitcnt lgkmcnt(3)
	v_mfma_f32_32x32x16_bf16 v[16:31], v[68:71], v[64:67], v[16:31]
	s_waitcnt lgkmcnt(1)
	v_mfma_f32_32x32x16_bf16 v[16:31], v[76:79], v[72:75], v[16:31]
	s_waitcnt lgkmcnt(0)
	s_waitcnt vmcnt(2)
	s_mov_b32 m0, s0
	s_waitcnt lgkmcnt(0)
	s_barrier
	v_lshl_add_u64 v[68:69], v[164:165], 0, s[16:17]
	global_load_lds_dwordx4 v[68:69], off
	v_lshl_add_u64 v[68:69], v[166:167], 0, s[18:19]
	s_mov_b32 m0, s1
	s_nop 0
	global_load_lds_dwordx4 v[68:69], off
	ds_read_b128 v[68:71], v201 offset:40960
	ds_read_b128 v[188:191], v201 offset:45056
	v_mfma_f32_32x32x16_bf16 v[0:15], v[174:177], v[64:67], v[0:15]
	ds_read_b128 v[64:67], v202 offset:40960
	ds_read_b128 v[174:177], v202 offset:45056
	v_mov_b64_e32 v[146:147], s[38:39]
	v_mov_b64_e32 v[144:145], s[36:37]
	v_exp_f32_e32 v192, v112
	v_exp_f32_e32 v193, v113
	v_exp_f32_e32 v194, v114
	v_exp_f32_e32 v195, v115
	s_waitcnt lgkmcnt(3)
	v_mfma_f32_32x32x16_bf16 v[80:95], v[68:71], v[132:135], v[48:63]
	v_mfma_f32_32x32x16_bf16 v[32:47], v[144:147], v[180:183], v[32:47]
	v_mfma_f32_32x32x16_bf16 v[0:15], v[184:187], v[72:75], v[0:15]
	ds_read_b128 v[112:115], v204 offset:40960
	ds_read_b128 v[180:183], v204 offset:45056
	s_waitcnt lgkmcnt(3)
	v_mfma_f32_32x32x16_bf16 v[80:95], v[64:67], v[128:131], v[80:95]
	v_exp_f32_e32 v116, v116
	v_exp_f32_e32 v117, v117
	v_exp_f32_e32 v118, v118
	v_exp_f32_e32 v119, v119
	v_cvt_pk_bf16_f32 v192, v192, v193
	v_cvt_pk_bf16_f32 v193, v194, v195
	v_mfma_f32_32x32x16_bf16 v[64:79], v[188:191], v[132:135], v[48:63]
	v_cvt_pk_bf16_f32 v194, v116, v117
	v_cvt_pk_bf16_f32 v195, v118, v119
	s_waitcnt lgkmcnt(1)
	v_mfma_f32_32x32x16_bf16 v[80:95], v[112:115], v[140:143], v[80:95]
	ds_read_b128 v[112:115], v203 offset:40960
	ds_read_b128 v[116:119], v203 offset:45056
	v_exp_f32_e32 v120, v120
	v_exp_f32_e32 v121, v121
	v_exp_f32_e32 v122, v122
	v_exp_f32_e32 v123, v123
	v_mfma_f32_32x32x16_bf16 v[32:47], v[144:147], v[168:171], v[32:47]
	v_mfma_f32_32x32x16_bf16 v[64:79], v[174:177], v[128:131], v[64:79]
	v_cvt_pk_bf16_f32 v174, v120, v121
	v_cvt_pk_bf16_f32 v175, v122, v123
	s_waitcnt lgkmcnt(1)
	v_mfma_f32_32x32x16_bf16 v[80:95], v[112:115], v[136:139], v[80:95]
	v_exp_f32_e32 v112, v124
	v_exp_f32_e32 v113, v125
	v_exp_f32_e32 v114, v126
	v_exp_f32_e32 v115, v127
	v_cvt_pk_bf16_f32 v176, v112, v113
	v_cvt_pk_bf16_f32 v177, v114, v115
	ds_read_b128 v[112:115], v206 offset:28672
	ds_read_b128 v[120:123], v206 offset:32768
	v_mfma_f32_32x32x16_bf16 v[64:79], v[180:183], v[140:143], v[64:79]
	ds_read_b128 v[124:127], v205 offset:28672
	ds_read_b128 v[180:183], v205 offset:32768
	s_waitcnt lgkmcnt(2)
	v_mfma_f32_32x32x16_bf16 v[0:15], v[120:123], v[192:195], v[0:15]
	v_exp_f32_e32 v121, v96
	v_exp_f32_e32 v96, v97
	v_exp_f32_e32 v97, v98
	v_pk_add_f32 v[122:123], v[162:163], v[218:219]
	v_exp_f32_e32 v120, v99
	v_pk_add_f32 v[98:99], v[156:157], v[216:217]
	v_mfma_f32_32x32x16_bf16 v[16:31], v[112:115], v[192:195], v[16:31]
	v_add_f32_e64 v122, v222, v122
	v_add_f32_e64 v123, v223, v123
	v_add_f32_e64 v98, v220, v98
	v_add_f32_e64 v99, v221, v99
	v_exp_f32_e32 v163, v100
	v_exp_f32_e32 v184, v101
	v_exp_f32_e32 v185, v102
	v_exp_f32_e32 v162, v103
	ds_read_b128 v[100:103], v200 offset:28672
	v_pk_add_f32 v[122:123], v[226:227], v[122:123]
	v_pk_add_f32 v[98:99], v[224:225], v[98:99]
	v_pk_add_f32 v[122:123], v[230:231], v[122:123]
	v_pk_add_f32 v[98:99], v[228:229], v[98:99]
	v_pk_add_f32 v[168:169], v[122:123], v[96:97]
	v_pk_add_f32 v[156:157], v[98:99], v[120:121]
	v_cvt_pk_bf16_f32 v96, v121, v96
	v_cvt_pk_bf16_f32 v97, v97, v120
	v_cvt_pk_bf16_f32 v98, v163, v184
	v_cvt_pk_bf16_f32 v99, v185, v162
	s_waitcnt lgkmcnt(1)
	v_mfma_f32_32x32x16_bf16 v[0:15], v[180:183], v[174:177], v[0:15]
	ds_read_b128 v[180:183], v200 offset:32768
	v_exp_f32_e32 v171, v104
	v_exp_f32_e32 v188, v105
	v_exp_f32_e32 v189, v106
	v_exp_f32_e32 v170, v107
	v_exp_f32_e32 v187, v108
	v_exp_f32_e32 v190, v109
	v_mfma_f32_32x32x16_bf16 v[64:79], v[116:119], v[136:139], v[64:79]
	v_exp_f32_e32 v191, v110
	v_exp_f32_e32 v186, v111
	v_cvt_pk_bf16_f32 v104, v171, v188
	v_cvt_pk_bf16_f32 v105, v189, v170
	v_cvt_pk_bf16_f32 v106, v187, v190
	v_cvt_pk_bf16_f32 v107, v191, v186
	v_mfma_f32_32x32x16_bf16 v[16:31], v[124:127], v[174:177], v[16:31]
	ds_read_b128 v[108:111], v151 offset:28672
	ds_read_b128 v[218:221], v151 offset:32768
	s_waitcnt lgkmcnt(3)
	v_mfma_f32_32x32x16_bf16 v[16:31], v[100:103], v[96:99], v[16:31]
	s_waitcnt lgkmcnt(1)
	v_mfma_f32_32x32x16_bf16 v[16:31], v[108:111], v[104:107], v[16:31]
	s_waitcnt lgkmcnt(0)
	s_waitcnt vmcnt(2)
	s_mov_b32 m0, s4
	s_waitcnt lgkmcnt(0)
	s_barrier
	v_lshl_add_u64 v[100:101], v[164:165], 0, s[34:35]
	global_load_lds_dwordx4 v[100:101], off
	v_lshl_add_u64 v[100:101], v[166:167], 0, s[42:43]
	s_mov_b32 m0, s5
	s_add_i32 s11, 0, 0x10000
	global_load_lds_dwordx4 v[100:101], off
	ds_read_b128 v[100:103], v201 offset:61440
	v_add_u32_e32 v215, s11, v207
	ds_read_b128 v[222:225], v215
	v_mfma_f32_32x32x16_bf16 v[0:15], v[180:183], v[96:99], v[0:15]
	ds_read_b128 v[96:99], v202 offset:61440
	v_add_u32_e32 v216, s11, v208
	ds_read_b128 v[180:183], v216
	v_exp_f32_e32 v226, v80
	v_exp_f32_e32 v227, v81
	v_exp_f32_e32 v228, v82
	v_exp_f32_e32 v229, v83
	v_mfma_f32_32x32x16_bf16 v[32:47], v[144:147], v[192:195], v[32:47]
	v_mfma_f32_32x32x16_bf16 v[0:15], v[218:221], v[104:107], v[0:15]
	ds_read_b128 v[80:83], v204 offset:61440
	s_waitcnt lgkmcnt(4)
	v_mfma_f32_32x32x16_bf16 v[112:127], v[100:103], v[132:135], v[48:63]
	v_add_u32_e32 v217, s11, v209
	ds_read_b128 v[192:195], v217
	v_exp_f32_e32 v84, v84
	v_exp_f32_e32 v85, v85
	v_exp_f32_e32 v86, v86
	v_exp_f32_e32 v87, v87
	v_cvt_pk_bf16_f32 v220, v226, v227
	s_waitcnt lgkmcnt(3)
	v_mfma_f32_32x32x16_bf16 v[112:127], v[96:99], v[128:131], v[112:127]
	v_cvt_pk_bf16_f32 v221, v228, v229
	v_mfma_f32_32x32x16_bf16 v[96:111], v[222:225], v[132:135], v[48:63]
	v_cvt_pk_bf16_f32 v222, v84, v85
	v_cvt_pk_bf16_f32 v223, v86, v87
	v_mfma_f32_32x32x16_bf16 v[32:47], v[144:147], v[174:177], v[32:47]
	v_add_u32_e32 v218, s11, v210
	v_exp_f32_e32 v88, v88
	v_exp_f32_e32 v89, v89
	v_exp_f32_e32 v90, v90
	v_exp_f32_e32 v91, v91
	s_waitcnt lgkmcnt(1)
	v_mfma_f32_32x32x16_bf16 v[112:127], v[80:83], v[140:143], v[112:127]
	ds_read_b128 v[80:83], v203 offset:61440
	ds_read_b128 v[84:87], v218
	s_waitcnt lgkmcnt(1)
	v_mfma_f32_32x32x16_bf16 v[112:127], v[80:83], v[136:139], v[112:127]
	v_exp_f32_e32 v80, v92
	v_exp_f32_e32 v81, v93
	v_exp_f32_e32 v82, v94
	v_exp_f32_e32 v83, v95
	v_cvt_pk_bf16_f32 v174, v88, v89
	v_cvt_pk_bf16_f32 v175, v90, v91
	v_cvt_pk_bf16_f32 v176, v80, v81
	v_mfma_f32_32x32x16_bf16 v[96:111], v[180:183], v[128:131], v[96:111]
	v_cvt_pk_bf16_f32 v177, v82, v83
	ds_read_b128 v[80:83], v206 offset:49152
	ds_read_b128 v[88:91], v206 offset:53248
	v_mfma_f32_32x32x16_bf16 v[96:111], v[192:195], v[140:143], v[96:111]
	ds_read_b128 v[92:95], v205 offset:49152
	ds_read_b128 v[180:183], v205 offset:53248
	s_waitcnt lgkmcnt(2)
	v_mfma_f32_32x32x16_bf16 v[0:15], v[88:91], v[220:223], v[0:15]
	v_exp_f32_e32 v193, v64
	v_exp_f32_e32 v194, v65
	v_exp_f32_e32 v195, v66
	v_exp_f32_e32 v192, v67
	v_exp_f32_e32 v229, v68
	v_exp_f32_e32 v230, v69
	v_mfma_f32_32x32x16_bf16 v[16:31], v[80:83], v[220:223], v[16:31]
	v_exp_f32_e32 v231, v70
	v_exp_f32_e32 v228, v71
	ds_read_b128 v[68:71], v200 offset:49152
	v_cvt_pk_bf16_f32 v64, v193, v194
	v_cvt_pk_bf16_f32 v65, v195, v192
	v_cvt_pk_bf16_f32 v66, v229, v230
	v_cvt_pk_bf16_f32 v67, v231, v228
	s_waitcnt lgkmcnt(1)
	v_mfma_f32_32x32x16_bf16 v[0:15], v[180:183], v[174:177], v[0:15]
	ds_read_b128 v[180:183], v200 offset:53248
	v_exp_f32_e32 v233, v72
	v_exp_f32_e32 v234, v73
	v_exp_f32_e32 v235, v74
	v_exp_f32_e32 v232, v75
	v_exp_f32_e32 v237, v76
	v_exp_f32_e32 v238, v77
	v_mfma_f32_32x32x16_bf16 v[16:31], v[92:95], v[174:177], v[16:31]
	v_exp_f32_e32 v239, v78
	v_exp_f32_e32 v236, v79
	v_cvt_pk_bf16_f32 v72, v233, v234
	v_cvt_pk_bf16_f32 v73, v235, v232
	v_cvt_pk_bf16_f32 v74, v237, v238
	v_cvt_pk_bf16_f32 v75, v239, v236
	v_mfma_f32_32x32x16_bf16 v[96:111], v[84:87], v[136:139], v[96:111]
	ds_read_b128 v[76:79], v151 offset:49152
	ds_read_b128 v[224:227], v151 offset:53248
	s_waitcnt lgkmcnt(3)
	v_mfma_f32_32x32x16_bf16 v[16:31], v[68:71], v[64:67], v[16:31]
	s_waitcnt lgkmcnt(1)
	v_mfma_f32_32x32x16_bf16 v[16:31], v[76:79], v[72:75], v[16:31]
	s_waitcnt lgkmcnt(0)
	s_waitcnt vmcnt(2)
	s_mov_b32 m0, s6
	s_waitcnt lgkmcnt(0)
	s_barrier
; template <int TYPE, bool FIXREF>
; DI void attn_dense_unit(const Params& p, int layer, int head, int qb, char* lds, float bref) {
;     ...
;   for (int t = 0; t < NT - 4; t += 4) {
;     STEP(sA0, sA1, sB0, sB1, t, true, true, R0, R1, R3);
;     STEP(sB0, sB1, sA0, sA1, t + 1, true, true, R1, R2, R0);
;     STEP(sA0, sA1, sB0, sB1, t + 2, true, true, R2, R3, R1);
;     STEP(sB0, sB1, sA0, sA1, t + 3, true, true, R3, R0, R2);
;   }
	v_lshl_add_u64 v[68:69], v[164:165], 0, s[44:45]
	global_load_lds_dwordx4 v[68:69], off
	v_lshl_add_u64 v[68:69], v[166:167], 0, s[46:47]
	s_mov_b32 m0, s7
	s_nop 0
	global_load_lds_dwordx4 v[68:69], off
	ds_read_b128 v[68:71], v201
	ds_read_b128 v[164:167], v201 offset:4096
	v_mfma_f32_32x32x16_bf16 v[0:15], v[180:183], v[64:67], v[0:15]
	ds_read_b128 v[64:67], v202
	ds_read_b128 v[180:183], v202 offset:4096
	s_waitcnt lgkmcnt(3)
	v_mfma_f32_32x32x16_bf16 v[80:95], v[68:71], v[132:135], v[48:63]
	v_exp_f32_e32 v68, v112
	v_exp_f32_e32 v69, v113
	v_exp_f32_e32 v70, v114
	v_exp_f32_e32 v71, v115
	v_mfma_f32_32x32x16_bf16 v[32:47], v[144:147], v[220:223], v[32:47]
	v_mfma_f32_32x32x16_bf16 v[0:15], v[224:227], v[72:75], v[0:15]
	s_waitcnt lgkmcnt(1)
	v_mfma_f32_32x32x16_bf16 v[80:95], v[64:67], v[128:131], v[80:95]
	ds_read_b128 v[112:115], v204
	ds_read_b128 v[220:223], v204 offset:4096
	v_exp_f32_e32 v64, v116
	v_exp_f32_e32 v65, v117
	v_exp_f32_e32 v66, v118
	v_exp_f32_e32 v67, v119
	v_cvt_pk_bf16_f32 v116, v68, v69
	v_cvt_pk_bf16_f32 v117, v70, v71
	v_cvt_pk_bf16_f32 v118, v64, v65
	v_cvt_pk_bf16_f32 v119, v66, v67
	v_mfma_f32_32x32x16_bf16 v[64:79], v[164:167], v[132:135], v[48:63]
	s_waitcnt lgkmcnt(1)
	v_mfma_f32_32x32x16_bf16 v[80:95], v[112:115], v[140:143], v[80:95]
	ds_read_b128 v[112:115], v203
	ds_read_b128 v[224:227], v203 offset:4096
	v_exp_f32_e32 v120, v120
	v_exp_f32_e32 v121, v121
	v_exp_f32_e32 v122, v122
	v_exp_f32_e32 v123, v123
	v_mfma_f32_32x32x16_bf16 v[32:47], v[144:147], v[174:177], v[32:47]
	v_mfma_f32_32x32x16_bf16 v[64:79], v[180:183], v[128:131], v[64:79]
	v_add_u32_e32 v166, 0, v211
	v_add_u32_e32 v167, s11, v211
	s_waitcnt lgkmcnt(1)
	v_mfma_f32_32x32x16_bf16 v[80:95], v[112:115], v[136:139], v[80:95]
	v_exp_f32_e32 v114, v124
	v_exp_f32_e32 v115, v125
	v_exp_f32_e32 v124, v126
	v_exp_f32_e32 v125, v127
	v_cvt_pk_bf16_f32 v112, v120, v121
	v_cvt_pk_bf16_f32 v113, v122, v123
	ds_read_b128 v[120:123], v166 offset:61440
	v_cvt_pk_bf16_f32 v114, v114, v115
	v_mfma_f32_32x32x16_bf16 v[64:79], v[220:223], v[140:143], v[64:79]
	v_cvt_pk_bf16_f32 v115, v124, v125
	ds_read_b128 v[124:127], v167
	s_waitcnt lgkmcnt(0)
	v_mfma_f32_32x32x16_bf16 v[0:15], v[124:127], v[116:119], v[0:15]
	v_add_u32_e32 v164, 0, v212
	ds_read_b128 v[174:177], v164 offset:61440
	v_add_u32_e32 v165, s11, v212
	ds_read_b128 v[180:183], v165
	v_exp_f32_e32 v127, v96
	v_exp_f32_e32 v222, v97
	v_exp_f32_e32 v223, v98
	v_mfma_f32_32x32x16_bf16 v[16:31], v[120:123], v[116:119], v[16:31]
	v_exp_f32_e32 v126, v99
	v_exp_f32_e32 v241, v100
	v_exp_f32_e32 v242, v101
	v_exp_f32_e32 v243, v102
	v_exp_f32_e32 v240, v103
	v_cvt_pk_bf16_f32 v96, v127, v222
	v_cvt_pk_bf16_f32 v97, v223, v126
	v_cvt_pk_bf16_f32 v98, v241, v242
	v_cvt_pk_bf16_f32 v99, v243, v240
	v_mfma_f32_32x32x16_bf16 v[32:47], v[144:147], v[116:119], v[32:47]
	v_exp_f32_e32 v125, v104
	v_exp_f32_e32 v104, v105
	v_exp_f32_e32 v105, v106
	v_exp_f32_e32 v124, v107
	v_pk_add_f32 v[106:107], v[162:163], v[156:157]
	v_pk_add_f32 v[168:169], v[184:185], v[168:169]
	v_pk_add_f32 v[106:107], v[170:171], v[106:107]
	v_pk_add_f32 v[168:169], v[188:189], v[168:169]
	v_pk_add_f32 v[106:107], v[186:187], v[106:107]
	v_pk_add_f32 v[168:169], v[190:191], v[168:169]
	v_pk_add_f32 v[106:107], v[106:107], v[192:193]
	s_waitcnt lgkmcnt(0)
	v_mfma_f32_32x32x16_bf16 v[0:15], v[180:183], v[112:115], v[0:15]
	v_add_f32_e64 v168, v168, v194
	v_add_f32_e64 v169, v169, v195
	v_add_f32_e64 v106, v228, v106
	v_add_f32_e64 v107, v229, v107
	v_add_f32_e64 v168, v230, v168
	v_add_f32_e64 v169, v231, v169
	v_pk_add_f32 v[106:107], v[232:233], v[106:107]
	v_pk_add_f32 v[168:169], v[234:235], v[168:169]
	v_pk_add_f32 v[106:107], v[236:237], v[106:107]
	v_add_u32_e32 v219, 0, v213
	v_mfma_f32_32x32x16_bf16 v[64:79], v[224:227], v[136:139], v[64:79]
	ds_read_b128 v[100:103], v219 offset:61440
	v_add_u32_e32 v220, s11, v213
	ds_read_b128 v[120:123], v220
	v_add_f32_e64 v168, v238, v168
	v_add_f32_e64 v169, v239, v169
	v_add_f32_e64 v106, v106, v126
	v_add_f32_e64 v107, v107, v127
	v_exp_f32_e32 v127, v108
	v_exp_f32_e32 v108, v109
	v_exp_f32_e32 v109, v110
	v_exp_f32_e32 v126, v111
	v_mfma_f32_32x32x16_bf16 v[16:31], v[174:177], v[112:115], v[16:31]
	v_add_f32_e64 v168, v168, v222
	v_add_f32_e64 v169, v169, v223
	v_add_f32_e64 v106, v240, v106
	v_add_f32_e64 v107, v241, v107
	v_pk_add_f32 v[168:169], v[242:243], v[168:169]
	v_pk_add_f32 v[106:107], v[124:125], v[106:107]
	v_pk_add_f32 v[168:169], v[104:105], v[168:169]
	v_mfma_f32_32x32x16_bf16 v[32:47], v[144:147], v[112:115], v[32:47]
	v_add_f32_e64 v162, v108, v168
	v_add_f32_e64 v163, v109, v169
	v_add_f32_e64 v156, v126, v106
	v_add_f32_e64 v157, v127, v107
	v_cvt_pk_bf16_f32 v104, v125, v104
	v_cvt_pk_bf16_f32 v105, v105, v124
	v_cvt_pk_bf16_f32 v106, v127, v108
	v_cvt_pk_bf16_f32 v107, v109, v126
	s_waitcnt lgkmcnt(1)
	v_mfma_f32_32x32x16_bf16 v[16:31], v[100:103], v[96:99], v[16:31]
	v_add_u32_e32 v168, 0, v214
	ds_read_b128 v[100:103], v168 offset:61440
	v_add_u32_e32 v169, s11, v214
	ds_read_b128 v[108:111], v169
	s_waitcnt lgkmcnt(2)
	v_mfma_f32_32x32x16_bf16 v[0:15], v[120:123], v[96:99], v[0:15]
	s_waitcnt lgkmcnt(1)
	v_mfma_f32_32x32x16_bf16 v[16:31], v[100:103], v[104:107], v[16:31]
	s_waitcnt lgkmcnt(0)
	v_mfma_f32_32x32x16_bf16 v[0:15], v[108:111], v[104:107], v[0:15]
	s_waitcnt vmcnt(2)
	s_waitcnt lgkmcnt(0)
	s_barrier
	s_add_i32 s9, s9, 4
	v_lshl_add_u64 v[158:159], v[158:159], 0, s[64:65]
	s_cmpk_lt_u32 s9, 0xf8
	v_lshl_add_u64 v[160:161], v[160:161], 0, s[66:67]
	s_cbranch_scc1 .LBB0_541
; template <int TYPE, bool FIXREF>
; DI void attn_dense_unit(const Params& p, int layer, int head, int qb, char* lds, float bref) {
;     ...
;   STEP(sA0, sA1, sB0, sB1, NT - 4, true, true, R0, R1, R3);
;   STEP(sB0, sB1, sA0, sA1, NT - 3, true, false, R1, R2, R0);
;   STEP(sA0, sA1, sB0, sB1, NT - 2, true, false, R2, R3, R1);
	s_mov_b64 s[0:1], 0xef10000
	s_mov_b32 m0, s10
	v_lshl_add_u64 v[96:97], v[154:155], 0, s[0:1]
	s_mov_b64 s[0:1], 0x7f80
	global_load_lds_dwordx4 v[96:97], off
	v_lshl_add_u64 v[96:97], v[152:153], 0, s[0:1]
	s_mov_b32 m0, s8
	s_mov_b64 s[88:89], 0x17618300
	global_load_lds_dwordx4 v[96:97], off
	ds_read_b128 v[96:99], v201 offset:20480
	ds_read_b128 v[144:147], v201 offset:24576
	s_mov_b64 s[62:63], 0x33ba200
	ds_read_b128 v[100:103], v202 offset:20480
	ds_read_b128 v[152:155], v202 offset:24576
	v_exp_f32_e32 v170, v80
	v_exp_f32_e32 v171, v81
	v_exp_f32_e32 v172, v82
	v_exp_f32_e32 v175, v83
	s_waitcnt lgkmcnt(0)
	v_mfma_f32_32x32x16_bf16 v[112:127], v[96:99], v[132:135], v[48:63]
	ds_read_b128 v[80:83], v204 offset:20480
	ds_read_b128 v[158:161], v204 offset:24576
	v_exp_f32_e32 v84, v84
	v_exp_f32_e32 v85, v85
	v_exp_f32_e32 v86, v86
	v_exp_f32_e32 v87, v87
	v_mfma_f32_32x32x16_bf16 v[112:127], v[100:103], v[128:131], v[112:127]
	v_cvt_pk_bf16_f32 v174, v170, v171
	v_cvt_pk_bf16_f32 v175, v172, v175
	v_cvt_pk_bf16_f32 v176, v84, v85
	v_cvt_pk_bf16_f32 v177, v86, v87
	v_mfma_f32_32x32x16_bf16 v[96:111], v[144:147], v[132:135], v[48:63]
	ds_read_b128 v[84:87], v203 offset:20480
	ds_read_b128 v[144:147], v203 offset:24576
	s_waitcnt lgkmcnt(0)
	v_mfma_f32_32x32x16_bf16 v[112:127], v[80:83], v[140:143], v[112:127]
	v_exp_f32_e32 v80, v88
	v_exp_f32_e32 v81, v89
	v_exp_f32_e32 v82, v90
	v_exp_f32_e32 v83, v91
	v_mfma_f32_32x32x16_bf16 v[112:127], v[84:87], v[136:139], v[112:127]
	v_exp_f32_e32 v84, v92
	v_exp_f32_e32 v85, v93
	v_exp_f32_e32 v86, v94
	v_exp_f32_e32 v87, v95
	v_cvt_pk_bf16_f32 v180, v80, v81
	v_cvt_pk_bf16_f32 v181, v82, v83
	v_cvt_pk_bf16_f32 v182, v84, v85
	v_mfma_f32_32x32x16_bf16 v[96:111], v[152:155], v[128:131], v[96:111]
	v_cvt_pk_bf16_f32 v183, v86, v87
	ds_read_b128 v[80:83], v206 offset:8192
	ds_read_b128 v[84:87], v206 offset:12288
	v_mfma_f32_32x32x16_bf16 v[96:111], v[158:161], v[140:143], v[96:111]
	s_waitcnt lgkmcnt(0)
	v_mfma_f32_32x32x16_bf16 v[0:15], v[84:87], v[174:177], v[0:15]
	ds_read_b128 v[88:91], v205 offset:8192
	ds_read_b128 v[92:95], v205 offset:12288
	v_exp_f32_e32 v153, v64
	v_exp_f32_e32 v171, v65
	v_exp_f32_e32 v184, v66
	v_exp_f32_e32 v152, v67
	v_exp_f32_e32 v170, v68
	v_exp_f32_e32 v172, v69
	v_exp_f32_e32 v186, v70
	v_exp_f32_e32 v154, v71
	v_mfma_f32_32x32x16_bf16 v[16:31], v[80:83], v[174:177], v[16:31]
	v_cvt_pk_bf16_f32 v64, v153, v171
	v_cvt_pk_bf16_f32 v65, v184, v152
	v_cvt_pk_bf16_f32 v66, v170, v172
	v_cvt_pk_bf16_f32 v67, v186, v154
	s_waitcnt lgkmcnt(0)
	v_mfma_f32_32x32x16_bf16 v[0:15], v[92:95], v[180:183], v[0:15]
	ds_read_b128 v[68:71], v200 offset:8192
	ds_read_b128 v[190:193], v200 offset:12288
	v_exp_f32_e32 v185, v72
	v_exp_f32_e32 v187, v73
	v_exp_f32_e32 v189, v74
	v_exp_f32_e32 v158, v75
	v_exp_f32_e32 v155, v76
	v_exp_f32_e32 v188, v77
	v_exp_f32_e32 v194, v78
	v_exp_f32_e32 v160, v79
	v_mfma_f32_32x32x16_bf16 v[96:111], v[144:147], v[136:139], v[96:111]
	v_cvt_pk_bf16_f32 v72, v185, v187
	v_cvt_pk_bf16_f32 v73, v189, v158
	v_cvt_pk_bf16_f32 v74, v155, v188
	v_cvt_pk_bf16_f32 v75, v194, v160
	v_mfma_f32_32x32x16_bf16 v[16:31], v[88:91], v[180:183], v[16:31]
	ds_read_b128 v[76:79], v151 offset:8192
	ds_read_b128 v[208:211], v151 offset:12288
	s_waitcnt lgkmcnt(0)
	v_mfma_f32_32x32x16_bf16 v[16:31], v[68:71], v[64:67], v[16:31]
	v_mfma_f32_32x32x16_bf16 v[16:31], v[76:79], v[72:75], v[16:31]
	s_waitcnt vmcnt(2)
	s_waitcnt lgkmcnt(0)
	s_barrier
	ds_read_b128 v[68:71], v201 offset:40960
	ds_read_b128 v[222:225], v201 offset:45056
	v_mfma_f32_32x32x16_bf16 v[0:15], v[190:193], v[64:67], v[0:15]
	v_mov_b64_e32 v[146:147], s[38:39]
	v_mov_b64_e32 v[144:145], s[36:37]
	v_exp_f32_e32 v159, v112
	v_exp_f32_e32 v161, v113
	v_exp_f32_e32 v195, v114
	v_exp_f32_e32 v207, v115
	v_mfma_f32_32x32x16_bf16 v[0:15], v[208:211], v[72:75], v[0:15]
	v_mfma_f32_32x32x16_bf16 v[32:47], v[144:147], v[174:177], v[32:47]
	ds_read_b128 v[64:67], v202 offset:40960
	ds_read_b128 v[174:177], v202 offset:45056
	s_waitcnt lgkmcnt(0)
	v_mfma_f32_32x32x16_bf16 v[80:95], v[68:71], v[132:135], v[48:63]
	ds_read_b128 v[112:115], v204 offset:40960
	ds_read_b128 v[190:193], v204 offset:45056
	v_exp_f32_e32 v116, v116
	v_exp_f32_e32 v117, v117
	v_exp_f32_e32 v118, v118
	v_exp_f32_e32 v119, v119
	v_mfma_f32_32x32x16_bf16 v[80:95], v[64:67], v[128:131], v[80:95]
	v_cvt_pk_bf16_f32 v208, v159, v161
	v_cvt_pk_bf16_f32 v209, v195, v207
	v_cvt_pk_bf16_f32 v210, v116, v117
	v_cvt_pk_bf16_f32 v211, v118, v119
	v_mfma_f32_32x32x16_bf16 v[64:79], v[222:225], v[132:135], v[48:63]
	s_waitcnt lgkmcnt(0)
	v_mfma_f32_32x32x16_bf16 v[80:95], v[112:115], v[140:143], v[80:95]
	ds_read_b128 v[112:115], v203 offset:40960
	ds_read_b128 v[222:225], v203 offset:45056
	v_exp_f32_e32 v116, v120
	v_exp_f32_e32 v117, v121
	v_exp_f32_e32 v118, v122
	v_exp_f32_e32 v119, v123
	v_mfma_f32_32x32x16_bf16 v[32:47], v[144:147], v[180:183], v[32:47]
	s_waitcnt lgkmcnt(0)
	v_mfma_f32_32x32x16_bf16 v[80:95], v[112:115], v[136:139], v[80:95]
	v_exp_f32_e32 v114, v126
	v_exp_f32_e32 v115, v127
	v_exp_f32_e32 v112, v124
	v_exp_f32_e32 v113, v125
	v_cvt_pk_bf16_f32 v120, v116, v117
	v_cvt_pk_bf16_f32 v123, v114, v115
	ds_read_b128 v[114:117], v206 offset:28672
	ds_read_b128 v[124:127], v206 offset:32768
	v_mfma_f32_32x32x16_bf16 v[64:79], v[174:177], v[128:131], v[64:79]
	v_cvt_pk_bf16_f32 v121, v118, v119
	v_cvt_pk_bf16_f32 v122, v112, v113
	v_mfma_f32_32x32x16_bf16 v[64:79], v[190:193], v[140:143], v[64:79]
	s_waitcnt lgkmcnt(0)
; template <int TYPE, bool FIXREF>
; DI void attn_dense_unit(const Params& p, int layer, int head, int qb, char* lds, float bref) {
;     ...
;   STEP(sB0, sB1, sA0, sA1, NT - 3, true, false, R1, R2, R0);
;   STEP(sA0, sA1, sB0, sB1, NT - 2, true, false, R2, R3, R1);
;   STEP(sB0, sB1, sA0, sA1, NT - 1, false, false, R3, R0, R2);
	v_mfma_f32_32x32x16_bf16 v[0:15], v[124:127], v[208:211], v[0:15]
	ds_read_b128 v[174:177], v205 offset:28672
	ds_read_b128 v[180:183], v205 offset:32768
	v_exp_f32_e32 v159, v96
	v_exp_f32_e32 v195, v97
	v_exp_f32_e32 v207, v98
	v_exp_f32_e32 v112, v99
	v_exp_f32_e32 v161, v100
	v_exp_f32_e32 v221, v101
	v_mfma_f32_32x32x16_bf16 v[16:31], v[114:117], v[208:211], v[16:31]
	v_exp_f32_e32 v226, v102
	v_exp_f32_e32 v114, v103
	v_cvt_pk_bf16_f32 v124, v159, v195
	v_cvt_pk_bf16_f32 v125, v207, v112
	v_cvt_pk_bf16_f32 v126, v161, v221
	v_cvt_pk_bf16_f32 v127, v226, v114
	s_waitcnt lgkmcnt(0)
	v_mfma_f32_32x32x16_bf16 v[0:15], v[180:183], v[120:123], v[0:15]
	ds_read_b128 v[96:99], v200 offset:28672
	ds_read_b128 v[180:183], v200 offset:32768
	v_exp_f32_e32 v113, v104
	v_exp_f32_e32 v227, v105
	v_exp_f32_e32 v228, v106
	v_exp_f32_e32 v116, v107
	v_exp_f32_e32 v115, v108
	v_exp_f32_e32 v229, v109
	v_exp_f32_e32 v230, v110
	v_exp_f32_e32 v118, v111
	v_mfma_f32_32x32x16_bf16 v[64:79], v[222:225], v[136:139], v[64:79]
	v_cvt_pk_bf16_f32 v190, v113, v227
	v_cvt_pk_bf16_f32 v191, v228, v116
	v_cvt_pk_bf16_f32 v192, v115, v229
	v_cvt_pk_bf16_f32 v193, v230, v118
	v_mfma_f32_32x32x16_bf16 v[16:31], v[174:177], v[120:123], v[16:31]
	ds_read_b128 v[100:103], v151 offset:28672
	ds_read_b128 v[174:177], v151 offset:32768
	s_waitcnt lgkmcnt(0)
	v_mfma_f32_32x32x16_bf16 v[16:31], v[96:99], v[124:127], v[16:31]
	v_mfma_f32_32x32x16_bf16 v[16:31], v[100:103], v[190:193], v[16:31]
	s_waitcnt vmcnt(0)
	s_waitcnt lgkmcnt(0)
	s_barrier
	ds_read_b128 v[222:225], v201 offset:61440
	ds_read_b128 v[212:215], v215
	v_mfma_f32_32x32x16_bf16 v[0:15], v[180:183], v[124:127], v[0:15]
	ds_read_b128 v[124:127], v202 offset:61440
	ds_read_b128 v[180:183], v216
	v_exp_f32_e32 v117, v80
	v_exp_f32_e32 v119, v81
	v_exp_f32_e32 v201, v82
	v_exp_f32_e32 v202, v83
	v_mfma_f32_32x32x16_bf16 v[0:15], v[174:177], v[190:193], v[0:15]
	s_waitcnt lgkmcnt(0)
	v_mfma_f32_32x32x16_bf16 v[96:111], v[222:225], v[132:135], v[48:63]
	v_mfma_f32_32x32x16_bf16 v[32:47], v[144:147], v[208:211], v[32:47]
	ds_read_b128 v[80:83], v204 offset:61440
	ds_read_b128 v[174:177], v217
	v_mfma_f32_32x32x16_bf16 v[96:111], v[124:127], v[128:131], v[96:111]
	v_exp_f32_e32 v124, v84
	v_exp_f32_e32 v125, v85
	v_exp_f32_e32 v126, v86
	v_exp_f32_e32 v87, v87
	v_cvt_pk_bf16_f32 v84, v117, v119
	v_cvt_pk_bf16_f32 v85, v201, v202
	v_cvt_pk_bf16_f32 v86, v124, v125
	v_cvt_pk_bf16_f32 v87, v126, v87
	v_mfma_f32_32x32x16_bf16 v[48:63], v[212:215], v[132:135], v[48:63]
	s_waitcnt lgkmcnt(0)
	v_mfma_f32_32x32x16_bf16 v[96:111], v[80:83], v[140:143], v[96:111]
	ds_read_b128 v[80:83], v203 offset:61440
	ds_read_b128 v[124:127], v218
	v_exp_f32_e32 v88, v88
	v_exp_f32_e32 v89, v89
	v_exp_f32_e32 v90, v90
	v_exp_f32_e32 v91, v91
	v_mfma_f32_32x32x16_bf16 v[32:47], v[144:147], v[120:123], v[32:47]
	s_waitcnt lgkmcnt(0)
	v_mfma_f32_32x32x16_bf16 v[96:111], v[80:83], v[136:139], v[96:111]
	v_exp_f32_e32 v82, v92
	v_exp_f32_e32 v83, v93
	v_exp_f32_e32 v92, v94
	v_exp_f32_e32 v93, v95
	v_cvt_pk_bf16_f32 v80, v88, v89
	v_cvt_pk_bf16_f32 v81, v90, v91
	v_cvt_pk_bf16_f32 v82, v82, v83
	v_mfma_f32_32x32x16_bf16 v[48:63], v[180:183], v[128:131], v[48:63]
	v_cvt_pk_bf16_f32 v83, v92, v93
	ds_read_b128 v[88:91], v206 offset:49152
	ds_read_b128 v[92:95], v206 offset:53248
	v_mfma_f32_32x32x16_bf16 v[48:63], v[174:177], v[140:143], v[48:63]
	s_waitcnt lgkmcnt(0)
	v_mfma_f32_32x32x16_bf16 v[0:15], v[92:95], v[84:87], v[0:15]
	ds_read_b128 v[120:123], v205 offset:49152
	ds_read_b128 v[128:131], v205 offset:53248
	v_exp_f32_e32 v117, v64
	v_exp_f32_e32 v132, v65
	v_exp_f32_e32 v133, v66
	v_exp_f32_e32 v64, v67
	v_exp_f32_e32 v119, v68
	v_exp_f32_e32 v134, v69
	v_exp_f32_e32 v135, v70
	v_exp_f32_e32 v66, v71
	v_mfma_f32_32x32x16_bf16 v[16:31], v[88:91], v[84:87], v[16:31]
	v_cvt_pk_bf16_f32 v88, v117, v132
	v_cvt_pk_bf16_f32 v89, v133, v64
	v_cvt_pk_bf16_f32 v90, v119, v134
	v_cvt_pk_bf16_f32 v91, v135, v66
	s_waitcnt lgkmcnt(0)
	v_mfma_f32_32x32x16_bf16 v[0:15], v[128:131], v[80:83], v[0:15]
	ds_read_b128 v[92:95], v200 offset:49152
	ds_read_b128 v[128:131], v200 offset:53248
	v_exp_f32_e32 v65, v72
	v_exp_f32_e32 v140, v73
	v_exp_f32_e32 v141, v74
	v_exp_f32_e32 v68, v75
	v_exp_f32_e32 v67, v76
	v_exp_f32_e32 v70, v79
	v_mfma_f32_32x32x16_bf16 v[48:63], v[124:127], v[136:139], v[48:63]
	v_exp_f32_e32 v124, v77
	v_exp_f32_e32 v125, v78
	v_cvt_pk_bf16_f32 v72, v65, v140
	v_cvt_pk_bf16_f32 v73, v141, v68
	v_cvt_pk_bf16_f32 v74, v67, v124
	v_cvt_pk_bf16_f32 v75, v125, v70
	v_mfma_f32_32x32x16_bf16 v[16:31], v[120:123], v[80:83], v[16:31]
	ds_read_b128 v[76:79], v151 offset:49152
	ds_read_b128 v[120:123], v151 offset:53248
	s_waitcnt lgkmcnt(0)
	v_mfma_f32_32x32x16_bf16 v[16:31], v[92:95], v[88:91], v[16:31]
	v_mfma_f32_32x32x16_bf16 v[16:31], v[76:79], v[72:75], v[16:31]
	s_waitcnt vmcnt(0)
	s_waitcnt lgkmcnt(0)
	s_barrier
; template <int TYPE, bool FIXREF>
; DI void attn_dense_unit(const Params& p, int layer, int head, int qb, char* lds, float bref) {
;     ...
;   STEP(sB0, sB1, sA0, sA1, NT - 1, false, false, R3, R0, R2);
;   lsum += ls0 + ls1 + ls2;
;   const float l = (NONES > 0 ? la[0] : 0.f) + lsum + __shfl_xor(lsum, 32);
	v_mfma_f32_32x32x16_bf16 v[0:15], v[128:131], v[88:91], v[0:15]
	v_exp_f32_e32 v69, v96
	v_exp_f32_e32 v71, v97
	v_exp_f32_e32 v77, v98
	v_exp_f32_e32 v78, v99
	v_mfma_f32_32x32x16_bf16 v[32:47], v[144:147], v[84:87], v[32:47]
	v_exp_f32_e32 v79, v100
	v_exp_f32_e32 v84, v101
	v_exp_f32_e32 v85, v102
	v_exp_f32_e32 v86, v103
	v_mfma_f32_32x32x16_bf16 v[32:47], v[144:147], v[80:83], v[32:47]
	v_cvt_pk_bf16_f32 v76, v69, v71
	v_cvt_pk_bf16_f32 v77, v77, v78
	v_cvt_pk_bf16_f32 v78, v79, v84
	v_cvt_pk_bf16_f32 v79, v85, v86
	v_exp_f32_e32 v69, v104
	v_exp_f32_e32 v71, v105
	v_exp_f32_e32 v80, v106
	v_exp_f32_e32 v81, v107
	v_exp_f32_e32 v82, v108
	v_exp_f32_e32 v83, v109
	v_exp_f32_e32 v84, v110
	v_exp_f32_e32 v85, v111
	v_mfma_f32_32x32x16_bf16 v[0:15], v[120:123], v[72:75], v[0:15]
	v_cvt_pk_bf16_f32 v73, v80, v81
	v_cvt_pk_bf16_f32 v74, v82, v83
	v_cvt_pk_bf16_f32 v75, v84, v85
	ds_read_b128 v[80:83], v166 offset:61440
	ds_read_b128 v[84:87], v167
	v_cvt_pk_bf16_f32 v72, v69, v71
	s_waitcnt lgkmcnt(0)
	v_mfma_f32_32x32x16_bf16 v[0:15], v[84:87], v[76:79], v[0:15]
	ds_read_b128 v[84:87], v164 offset:61440
	ds_read_b128 v[88:91], v165
	v_mfma_f32_32x32x16_bf16 v[16:31], v[80:83], v[76:79], v[16:31]
	v_exp_f32_e32 v69, v48
	v_add_f32_e32 v48, v163, v184
	v_add_f32_e32 v48, v186, v48
	v_add_f32_e32 v48, v189, v48
	v_add_f32_e32 v48, v194, v48
	v_add_f32_e32 v48, v48, v207
	v_add_f32_e32 v48, v226, v48
	v_add_f32_e32 v48, v228, v48
	v_add_f32_e32 v48, v230, v48
	s_waitcnt lgkmcnt(0)
	v_mfma_f32_32x32x16_bf16 v[0:15], v[88:91], v[72:75], v[0:15]
	v_exp_f32_e32 v88, v59
	v_exp_f32_e32 v59, v50
	v_add_f32_e32 v48, v48, v133
	v_exp_f32_e32 v71, v52
	v_exp_f32_e32 v52, v53
	v_exp_f32_e32 v53, v54
	v_add_f32_e32 v48, v135, v48
	v_mfma_f32_32x32x16_bf16 v[16:31], v[84:87], v[72:75], v[16:31]
	v_exp_f32_e32 v85, v56
	v_exp_f32_e32 v56, v58
	v_add_f32_e32 v48, v141, v48
	v_exp_f32_e32 v58, v62
	v_add_f32_e32 v48, v125, v48
	v_add_f32_e32 v48, v48, v59
	v_add_f32_e32 v48, v53, v48
	v_add_f32_e32 v48, v56, v48
	v_add_f32_e32 v91, v58, v48
	v_add_f32_e32 v48, v162, v171
	v_add_f32_e32 v48, v172, v48
	v_add_f32_e32 v48, v187, v48
	v_add_f32_e32 v48, v188, v48
	v_add_f32_e32 v48, v48, v195
	v_add_f32_e32 v48, v221, v48
	v_add_f32_e32 v48, v227, v48
	v_add_f32_e32 v48, v229, v48
	v_exp_f32_e32 v86, v55
	v_exp_f32_e32 v55, v49
	v_add_f32_e32 v48, v48, v132
	v_add_f32_e32 v48, v134, v48
	v_exp_f32_e32 v54, v57
	v_add_f32_e32 v48, v140, v48
	v_exp_f32_e32 v57, v61
	v_add_f32_e32 v48, v124, v48
	v_mfma_f32_32x32x16_bf16 v[32:47], v[144:147], v[76:79], v[32:47]
	v_add_f32_e32 v48, v48, v55
	v_add_f32_e32 v48, v52, v48
	v_add_f32_e32 v48, v54, v48
	ds_read_b128 v[80:83], v219 offset:61440
	ds_read_b128 v[92:95], v220
	v_add_f32_e32 v89, v57, v48
	v_add_f32_e32 v48, v157, v153
	v_exp_f32_e32 v84, v51
	v_exp_f32_e32 v90, v63
	v_exp_f32_e32 v87, v60
	v_add_f32_e32 v153, v170, v48
	v_mov_b32_e32 v157, v185
	v_pk_add_f32 v[48:49], v[156:157], v[152:153]
	v_mfma_f32_32x32x16_bf16 v[32:47], v[144:147], v[72:75], v[32:47]
	v_add_f32_e64 v48, v154, v48
	v_add_f32_e64 v49, v155, v49
	v_add_f32_e64 v48, v158, v48
	v_add_f32_e64 v49, v159, v49
	v_add_f32_e64 v50, v160, v48
	v_add_f32_e64 v51, v161, v49
	s_nop 5
	v_cvt_pk_bf16_f32 v34, v69, v55
	v_cvt_pk_bf16_f32 v35, v59, v84
	v_cvt_pk_bf16_f32 v36, v71, v52
	v_cvt_pk_bf16_f32 v37, v53, v86
	v_cvt_pk_bf16_f32 v38, v85, v54
	v_cvt_pk_bf16_f32 v39, v56, v88
	v_cvt_pk_bf16_f32 v40, v87, v57
	v_cvt_pk_bf16_f32 v41, v58, v90
	s_waitcnt lgkmcnt(0)
	v_mfma_f32_32x32x16_bf16 v[0:15], v[92:95], v[34:37], v[0:15]
	ds_read_b128 v[42:45], v168 offset:61440
	ds_read_b128 v[46:49], v169
	v_mfma_f32_32x32x16_bf16 v[16:31], v[80:83], v[34:37], v[16:31]
	s_waitcnt lgkmcnt(0)
	v_mfma_f32_32x32x16_bf16 v[0:15], v[46:49], v[38:41], v[0:15]
	v_mfma_f32_32x32x16_bf16 v[16:31], v[42:45], v[38:41], v[16:31]
	v_add_f32_e64 v34, v50, v112
	v_add_f32_e64 v35, v51, v113
	v_lshlrev_b32_e32 v172, 1, v150
	v_add_f32_e64 v34, v114, v34
	v_add_f32_e64 v35, v115, v35
	s_waitcnt vmcnt(0)
	s_waitcnt lgkmcnt(0)
	s_barrier
; DI unsigned pk2(float lo, float hi) { f32x2 v = {lo, hi}; bf16x2_t b = __builtin_convertvector(v, bf16x2_t); return __builtin_bit_cast(unsigned, b); }
; DI void store_o_wide(bf16_t* rowp, const f32x16& o, float inv, int h) {
; #pragma unroll
;   for (int pr = 0; pr < 2; ++pr) {
;     const int g = 2 * pr;
;     const unsigned ax = pk2(o[4 * g] * inv, o[4 * g + 1] * inv), ay = pk2(o[4 * g + 2] * inv, o[4 * g + 3] * inv);
;     const unsigned bx = pk2(o[4 * g + 4] * inv, o[4 * g + 5] * inv), by = pk2(o[4 * g + 6] * inv, o[4 * g + 7] * inv);
;     const auto sx = __builtin_amdgcn_permlane32_swap(ax, bx, false, false);
;     const auto sy = __builtin_amdgcn_permlane32_swap(ay, by, false, false);
;     const u32x4 w = {sx[0], sy[0], sx[1], sy[1]};
;     *(u32x4*)(rowp + 8 * (g + h)) = w;
;   }
; }
; template <int TYPE, bool FIXREF>
; DI void attn_dense_unit(const Params& p, int layer, int head, int qb, char* lds, float bref) {
;     ...
;   lsum += ls0 + ls1 + ls2;
;   const float l = (NONES > 0 ? la[0] : 0.f) + lsum + __shfl_xor(lsum, 32);
;     ...
;   const float inv = 1.0f / l;
;   bf16_t* op = O + (size_t)q * 512 + head * 64;
;   store_o_wide(op, o0, inv, h); store_o_wide(op + 32, o1, inv, h);
	v_pk_add_f32 v[34:35], v[116:117], v[34:35]
	s_nop 0
	v_pk_add_f32 v[34:35], v[118:119], v[34:35]
	s_nop 0
	v_pk_add_f32 v[34:35], v[34:35], v[64:65]
	s_nop 0
	v_pk_add_f32 v[34:35], v[66:67], v[34:35]
	s_nop 0
	v_pk_add_f32 v[34:35], v[68:69], v[34:35]
	s_nop 0
	v_pk_add_f32 v[34:35], v[70:71], v[34:35]
	s_nop 0
	v_pk_add_f32 v[34:35], v[34:35], v[84:85]
	s_nop 0
	v_pk_add_f32 v[34:35], v[86:87], v[34:35]
	s_nop 0
	v_pk_add_f32 v[34:35], v[88:89], v[34:35]
	s_nop 0
	v_pk_add_f32 v[34:35], v[90:91], v[34:35]
	s_nop 0
	v_add_f32_e32 v33, v34, v35
	ds_bpermute_b32 v34, v199, v33
	v_add_f32_e32 v32, v33, v32
	s_waitcnt lgkmcnt(0)
	v_add_f32_e32 v32, v32, v34
	v_div_scale_f32 v33, s[0:1], v32, v32, 1.0
	v_rcp_f32_e32 v34, v33
	v_readlane_b32 s0, v253, 13
	v_readlane_b32 s1, v253, 14
	v_fma_f32 v35, -v33, v34, 1.0
	v_fmac_f32_e32 v34, v35, v34
	v_div_scale_f32 v35, vcc, 1.0, v32, 1.0
	v_mul_f32_e32 v36, v35, v34
	v_fma_f32 v37, -v33, v36, v35
	v_fmac_f32_e32 v36, v37, v34
	v_fma_f32 v33, -v33, v36, v35
	v_div_fmas_f32 v33, v33, v34, v36
	v_div_fixup_f32 v32, v33, v32, 1.0
	v_lshlrev_b64 v[34:35], 10, v[148:149]
	v_pk_mul_f32 v[16:17], v[16:17], v[32:33] op_sel_hi:[1,0]
	v_pk_mul_f32 v[18:19], v[18:19], v[32:33] op_sel_hi:[1,0]
	v_pk_mul_f32 v[0:1], v[0:1], v[32:33] op_sel_hi:[1,0]
	v_pk_mul_f32 v[2:3], v[2:3], v[32:33] op_sel_hi:[1,0]
	v_lshl_add_u64 v[34:35], s[0:1], 0, v[34:35]
	v_cvt_pk_bf16_f32 v16, v16, v17
	v_cvt_pk_bf16_f32 v17, v18, v19
	v_pk_mul_f32 v[18:19], v[20:21], v[32:33] op_sel_hi:[1,0]
	v_pk_mul_f32 v[20:21], v[22:23], v[32:33] op_sel_hi:[1,0]
	v_cvt_pk_bf16_f32 v0, v0, v1
	v_cvt_pk_bf16_f32 v1, v2, v3
	v_pk_mul_f32 v[2:3], v[4:5], v[32:33] op_sel_hi:[1,0]
	v_pk_mul_f32 v[4:5], v[6:7], v[32:33] op_sel_hi:[1,0]
	v_lshl_add_u64 v[34:35], v[34:35], 0, s[68:69]
	v_cvt_pk_bf16_f32 v18, v18, v19
	v_cvt_pk_bf16_f32 v19, v20, v21
	v_cvt_pk_bf16_f32 v2, v2, v3
	v_cvt_pk_bf16_f32 v3, v4, v5
	v_permlane32_swap_b32_e32 v16, v18
	v_permlane32_swap_b32_e32 v17, v19
	v_lshl_add_u64 v[20:21], v[34:35], 0, v[172:173]
	v_permlane32_swap_b32_e32 v0, v2
	v_permlane32_swap_b32_e32 v1, v3
	global_store_dwordx4 v[20:21], v[16:19], off
	global_store_dwordx4 v[20:21], v[0:3], off offset:64
	v_pk_mul_f32 v[22:23], v[30:31], v[32:33] op_sel_hi:[1,0]
	v_pk_mul_f32 v[16:17], v[24:25], v[32:33] op_sel_hi:[1,0]
	v_pk_mul_f32 v[18:19], v[26:27], v[32:33] op_sel_hi:[1,0]
	v_pk_mul_f32 v[0:1], v[8:9], v[32:33] op_sel_hi:[1,0]
	v_pk_mul_f32 v[2:3], v[10:11], v[32:33] op_sel_hi:[1,0]
	v_cvt_pk_bf16_f32 v16, v16, v17
	v_cvt_pk_bf16_f32 v17, v18, v19
	v_pk_mul_f32 v[18:19], v[28:29], v[32:33] op_sel_hi:[1,0]
	v_cvt_pk_bf16_f32 v0, v0, v1
	v_cvt_pk_bf16_f32 v1, v2, v3
	v_pk_mul_f32 v[2:3], v[12:13], v[32:33] op_sel_hi:[1,0]
	v_pk_mul_f32 v[6:7], v[14:15], v[32:33] op_sel_hi:[1,0]
	v_cvt_pk_bf16_f32 v18, v18, v19
	v_cvt_pk_bf16_f32 v19, v22, v23
	v_cvt_pk_bf16_f32 v2, v2, v3
	v_cvt_pk_bf16_f32 v3, v6, v7
	v_permlane32_swap_b32_e32 v16, v18
	v_permlane32_swap_b32_e32 v17, v19
	v_lshl_add_u64 v[4:5], v[20:21], 0, 64
	v_permlane32_swap_b32_e32 v0, v2
	v_permlane32_swap_b32_e32 v1, v3
	global_store_dwordx4 v[20:21], v[16:19], off offset:32

.LBB0_557:
	ds_read_b128 v[32:35], v199 offset:20480
	ds_read_b128 v[42:45], v199 offset:24576
	ds_read_b128 v[38:41], v200 offset:20480
	ds_read_b128 v[188:191], v200 offset:24576
	s_add_u32 s4, s92, 0x15648000
	s_addc_u32 s5, s93, 0
	s_mov_b32 m0, s9
	s_nop 0
	global_load_lds_dwordx4 v164, s[4:5]
	s_waitcnt lgkmcnt(3)
	v_mfma_f32_32x32x16_bf16 v[112:127], v[32:35], v[132:135], v[48:63]
	s_setprio 1
	v_exp_f32_e32 v34, v80
	v_exp_f32_e32 v37, v81
	v_exp_f32_e32 v36, v82
	v_exp_f32_e32 v35, v83
	ds_read_b128 v[80:83], v201 offset:20480
	ds_read_b128 v[220:223], v201 offset:24576
	s_setprio 0
	s_add_u32 s4, s92, 0x16618180
	s_addc_u32 s5, s93, 0
	s_mov_b32 m0, s7
	s_nop 0
	global_load_lds_dwordx4 v160, s[4:5]
	s_waitcnt lgkmcnt(3)
	v_mfma_f32_32x32x16_bf16 v[112:127], v[38:41], v[128:131], v[112:127]
	s_setprio 1
	v_mfma_f32_32x32x16_bf16 v[96:111], v[42:45], v[132:135], v[48:63]
	ds_read_b128 v[44:47], v202 offset:20480
	ds_read_b128 v[224:227], v202 offset:24576
	v_exp_f32_e32 v32, v84
	v_exp_f32_e32 v41, v85
	v_exp_f32_e32 v40, v86
	v_exp_f32_e32 v33, v87
	s_setprio 0
	v_cvt_pk_bf16_f32 v84, v34, v37
	v_cvt_pk_bf16_f32 v85, v36, v35
	v_cvt_pk_bf16_f32 v86, v32, v41
	v_cvt_pk_bf16_f32 v87, v40, v33
	s_and_b64 vcc, exec, s[44:45]
	s_cbranch_vccnz .Lmy_a1_norope
	s_add_u32 s4, s92, 0x30e8500
	s_addc_u32 s5, s93, 0
	s_mov_b32 m0, s6
	s_nop 0
	global_load_lds_dwordx4 v162, s[4:5]
.Lmy_a1_norope:
	s_waitcnt lgkmcnt(3)
	v_mfma_f32_32x32x16_bf16 v[112:127], v[80:83], v[144:147], v[112:127]
	s_setprio 1
	v_exp_f32_e32 v38, v88
	v_exp_f32_e32 v43, v89
	v_exp_f32_e32 v42, v90
	v_exp_f32_e32 v39, v91
	ds_read_b128 v[88:91], v210 offset:36864
	ds_read_b128 v[228:231], v210 offset:38912
	s_setprio 0
	s_waitcnt lgkmcnt(3)
	v_mfma_f32_32x32x16_bf16 v[112:127], v[44:47], v[140:143], v[112:127]
	s_setprio 1
	v_mfma_f32_32x32x16_bf16 v[96:111], v[188:191], v[128:131], v[96:111]
	v_exp_f32_e32 v44, v92
	v_exp_f32_e32 v81, v93
	v_exp_f32_e32 v80, v94
	v_exp_f32_e32 v45, v95
	v_mfma_f32_32x32x16_bf16 v[96:111], v[220:223], v[144:147], v[96:111]
	ds_read_b128 v[188:191], v211 offset:36864
	ds_read_b128 v[220:223], v211 offset:38912
	s_setprio 0
	v_cvt_pk_bf16_f32 v92, v38, v43
	v_cvt_pk_bf16_f32 v93, v42, v39
	v_cvt_pk_bf16_f32 v94, v44, v81
	v_cvt_pk_bf16_f32 v95, v80, v45
	s_waitcnt lgkmcnt(3)
	v_mfma_f32_32x32x16_bf16 v[112:127], v[88:91], v[148:151], v[112:127]
	s_setprio 1
	v_exp_f32_e32 v46, v64
	v_exp_f32_e32 v83, v65
	v_exp_f32_e32 v82, v66
	v_exp_f32_e32 v47, v67
	s_setprio 0
	s_waitcnt lgkmcnt(1)
	v_mfma_f32_32x32x16_bf16 v[112:127], v[188:191], v[136:139], v[112:127]
	s_setprio 1
	v_mfma_f32_32x32x16_bf16 v[96:111], v[224:227], v[140:143], v[96:111]
	v_exp_f32_e32 v64, v68
	v_exp_f32_e32 v67, v69
	v_exp_f32_e32 v66, v70
	v_exp_f32_e32 v65, v71
	ds_read_b128 v[68:71], v206 offset:8192
	ds_read_b128 v[88:91], v206 offset:12288
	v_mfma_f32_32x32x16_bf16 v[96:111], v[228:231], v[148:151], v[96:111]
	ds_read_b128 v[224:227], v205 offset:8192
	ds_read_b128 v[228:231], v205 offset:12288
	s_setprio 0
	v_cvt_pk_bf16_f32 v188, v46, v83
	v_cvt_pk_bf16_f32 v189, v82, v47
	v_cvt_pk_bf16_f32 v190, v64, v67
	v_cvt_pk_bf16_f32 v191, v66, v65
	s_waitcnt lgkmcnt(3)
	v_mfma_f32_32x32x16_bf16 v[0:15], v[68:71], v[84:87], v[0:15]
	ds_read_b128 v[232:235], v204 offset:8192
	ds_read_b128 v[236:239], v204 offset:12288
	s_setprio 1
	v_exp_f32_e32 v68, v72
	v_exp_f32_e32 v71, v73
	v_exp_f32_e32 v70, v74
	v_exp_f32_e32 v69, v75
	s_setprio 0
	s_waitcnt lgkmcnt(3)
	v_mfma_f32_32x32x16_bf16 v[0:15], v[224:227], v[92:95], v[0:15]
	s_setprio 1
	v_mfma_f32_32x32x16_bf16 v[16:31], v[88:91], v[84:87], v[16:31]
	v_exp_f32_e32 v72, v76
	v_exp_f32_e32 v75, v77
	v_exp_f32_e32 v74, v78
	v_exp_f32_e32 v73, v79
	v_mfma_f32_32x32x16_bf16 v[96:111], v[220:223], v[136:139], v[96:111]
	s_waitcnt lgkmcnt(2)
	v_mfma_f32_32x32x16_bf16 v[16:31], v[228:231], v[92:95], v[16:31]
	ds_read_b128 v[84:87], v203 offset:8192
	ds_read_b128 v[88:91], v203 offset:12288
	s_setprio 0
	v_cvt_pk_bf16_f32 v76, v68, v71
	v_cvt_pk_bf16_f32 v77, v70, v69
	v_cvt_pk_bf16_f32 v78, v72, v75
	v_cvt_pk_bf16_f32 v79, v74, v73
	s_waitcnt lgkmcnt(3)
	v_mfma_f32_32x32x16_bf16 v[0:15], v[232:235], v[188:191], v[0:15]
	v_max_f32_e32 v92, v112, v112
	v_max_f32_e32 v92, 0xf149f2ca, v92
	v_max3_f32 v93, v114, s72, v115
	v_max3_f32 v92, v92, v113, v116
	v_max3_f32 v93, v93, v118, v119
	v_max3_f32 v92, v92, v117, v120
	s_waitcnt lgkmcnt(2)
	v_mfma_f32_32x32x16_bf16 v[16:31], v[236:239], v[188:191], v[16:31]
	v_max3_f32 v93, v93, v122, v123
	v_max3_f32 v92, v92, v121, v124
	v_max3_f32 v93, v93, v126, v127
	s_waitcnt lgkmcnt(1)
	v_mfma_f32_32x32x16_bf16 v[0:15], v[84:87], v[76:79], v[0:15]
	v_max3_f32 v84, v92, v125, v96
	v_max3_f32 v85, v93, v98, v99
	v_max3_f32 v84, v84, v97, v100
	v_max3_f32 v85, v85, v102, v103
	v_max3_f32 v84, v84, v101, v104
	v_max3_f32 v85, v85, v106, v107
	v_max3_f32 v84, v84, v105, v108
	s_waitcnt lgkmcnt(0)
	v_mfma_f32_32x32x16_bf16 v[16:31], v[88:91], v[76:79], v[16:31]
	v_max3_f32 v85, v85, v110, v111
	v_max3_f32 v76, v84, v109, v85
	v_mov_b32_e32 v77, v76
	s_nop 1
	v_permlane32_swap_b32_e32 v76, v77
	s_waitcnt vmcnt(2)

.LBB0_564:
.LBB0_566:
	ds_read_b128 v[64:67], v199 offset:40960
	ds_read_b128 v[220:223], v199 offset:45056
	ds_read_b128 v[68:71], v200 offset:40960
	ds_read_b128 v[224:227], v200 offset:45056
	s_add_u32 s4, s92, 0x15658000
	s_addc_u32 s5, s93, 0
	s_mov_b32 m0, s43
	s_nop 0
	global_load_lds_dwordx4 v164, s[4:5]
	s_waitcnt lgkmcnt(3)
	v_mfma_f32_32x32x16_bf16 v[80:95], v[64:67], v[132:135], v[32:47]
	ds_read_b128 v[228:231], v201 offset:40960
	ds_read_b128 v[232:235], v201 offset:45056
	s_setprio 1
	v_exp_f32_e32 v112, v112
	v_exp_f32_e32 v189, v113
	v_exp_f32_e32 v188, v114
	v_exp_f32_e32 v113, v115
	s_setprio 0
	s_add_u32 s4, s92, 0x16618200
	s_addc_u32 s5, s93, 0
	s_mov_b32 m0, s70
	s_nop 0
	global_load_lds_dwordx4 v160, s[4:5]
	s_waitcnt lgkmcnt(3)
	v_mfma_f32_32x32x16_bf16 v[80:95], v[68:71], v[128:131], v[80:95]
	s_setprio 1
	v_mfma_f32_32x32x16_bf16 v[64:79], v[220:223], v[132:135], v[32:47]
	ds_read_b128 v[236:239], v202 offset:40960
	ds_read_b128 v[240:243], v202 offset:45056
	v_exp_f32_e32 v114, v116
	v_exp_f32_e32 v117, v117
	v_exp_f32_e32 v116, v118
	v_exp_f32_e32 v115, v119
	s_setprio 0
	v_cvt_pk_bf16_f32 v220, v112, v189
	v_cvt_pk_bf16_f32 v221, v188, v113
	v_cvt_pk_bf16_f32 v222, v114, v117
	v_cvt_pk_bf16_f32 v223, v116, v115
	s_and_b64 vcc, exec, s[44:45]
	s_cbranch_vccnz .Lmy_a2_norope
	s_add_u32 s4, s92, 0x31d8500
	s_addc_u32 s5, s93, 0
	s_add_i32 m0, s43, 0x4000
	s_nop 0
	global_load_lds_dwordx4 v162, s[4:5]
.Lmy_a2_norope:
	s_waitcnt lgkmcnt(3)
	v_mfma_f32_32x32x16_bf16 v[80:95], v[228:231], v[144:147], v[80:95]
	ds_read_b128 v[228:231], v210 offset:57344
	ds_read_b128 v[244:247], v210 offset:59392
	s_setprio 1
	v_exp_f32_e32 v118, v120
	v_exp_f32_e32 v191, v121
	v_exp_f32_e32 v190, v122
	v_exp_f32_e32 v119, v123
	s_setprio 0
	s_waitcnt lgkmcnt(3)
	v_mfma_f32_32x32x16_bf16 v[80:95], v[236:239], v[140:143], v[80:95]
	s_setprio 1
	v_mfma_f32_32x32x16_bf16 v[64:79], v[224:227], v[128:131], v[64:79]
	v_exp_f32_e32 v120, v124
	v_exp_f32_e32 v123, v125
	v_exp_f32_e32 v122, v126
	v_exp_f32_e32 v121, v127
	v_mfma_f32_32x32x16_bf16 v[64:79], v[232:235], v[144:147], v[64:79]
	ds_read_b128 v[232:235], v211 offset:57344
	ds_read_b128 v[236:239], v211 offset:59392
	s_setprio 0
	v_cvt_pk_bf16_f32 v224, v118, v191
	v_cvt_pk_bf16_f32 v225, v190, v119
	v_cvt_pk_bf16_f32 v226, v120, v123
	v_cvt_pk_bf16_f32 v227, v122, v121
	s_waitcnt lgkmcnt(3)
	v_mfma_f32_32x32x16_bf16 v[80:95], v[228:231], v[148:151], v[80:95]
	s_setprio 1
	v_exp_f32_e32 v96, v96
	v_exp_f32_e32 v125, v97
	v_exp_f32_e32 v124, v98
	v_exp_f32_e32 v97, v99
	s_setprio 0
	s_waitcnt lgkmcnt(1)
	v_mfma_f32_32x32x16_bf16 v[80:95], v[232:235], v[136:139], v[80:95]
	s_setprio 1
	v_mfma_f32_32x32x16_bf16 v[64:79], v[240:243], v[140:143], v[64:79]
	ds_read_b128 v[228:231], v206 offset:28672
	ds_read_b128 v[232:235], v206 offset:32768
	v_exp_f32_e32 v98, v100
	v_exp_f32_e32 v101, v101
	v_exp_f32_e32 v100, v102
	v_exp_f32_e32 v99, v103
	v_mfma_f32_32x32x16_bf16 v[64:79], v[244:247], v[148:151], v[64:79]
	ds_read_b128 v[244:247], v205 offset:28672
	ds_read_b128 v[180:183], v205 offset:32768
	s_setprio 0
	v_cvt_pk_bf16_f32 v240, v96, v125
	v_cvt_pk_bf16_f32 v241, v124, v97
	v_cvt_pk_bf16_f32 v242, v98, v101
	v_cvt_pk_bf16_f32 v243, v100, v99
	s_waitcnt lgkmcnt(3)
	v_mfma_f32_32x32x16_bf16 v[0:15], v[228:231], v[220:223], v[0:15]
	ds_read_b128 v[228:231], v204 offset:28672
	ds_read_b128 v[174:177], v204 offset:32768
	s_setprio 1
	v_exp_f32_e32 v102, v104
	v_exp_f32_e32 v105, v105
	v_exp_f32_e32 v104, v106
	v_exp_f32_e32 v103, v107
	s_setprio 0
	s_waitcnt lgkmcnt(3)
	v_mfma_f32_32x32x16_bf16 v[0:15], v[244:247], v[224:227], v[0:15]
	s_setprio 1
	v_mfma_f32_32x32x16_bf16 v[16:31], v[232:235], v[220:223], v[16:31]
	v_exp_f32_e32 v106, v108
	v_exp_f32_e32 v109, v109
	v_exp_f32_e32 v108, v110
	v_exp_f32_e32 v107, v111
	v_mfma_f32_32x32x16_bf16 v[64:79], v[236:239], v[136:139], v[64:79]
	s_waitcnt lgkmcnt(2)
	v_mfma_f32_32x32x16_bf16 v[16:31], v[180:183], v[224:227], v[16:31]
	ds_read_b128 v[220:223], v203 offset:28672
	ds_read_b128 v[224:227], v203 offset:32768
	s_setprio 0
	v_cvt_pk_bf16_f32 v180, v102, v105
	v_cvt_pk_bf16_f32 v181, v104, v103
	v_cvt_pk_bf16_f32 v182, v106, v109
	v_cvt_pk_bf16_f32 v183, v108, v107
	s_waitcnt lgkmcnt(3)
	v_mfma_f32_32x32x16_bf16 v[0:15], v[228:231], v[240:243], v[0:15]
	v_max_f32_e32 v110, v80, v80
	v_max_f32_e32 v110, 0xf149f2ca, v110
	v_max3_f32 v111, v82, s72, v83
	v_max3_f32 v110, v110, v81, v84
	v_max3_f32 v111, v111, v86, v87
	v_max3_f32 v110, v110, v85, v88
	s_waitcnt lgkmcnt(2)
	v_mfma_f32_32x32x16_bf16 v[16:31], v[174:177], v[240:243], v[16:31]
	v_max3_f32 v111, v111, v90, v91
	v_max3_f32 v110, v110, v89, v92
	v_max3_f32 v111, v111, v94, v95
	s_waitcnt lgkmcnt(1)
	v_mfma_f32_32x32x16_bf16 v[0:15], v[220:223], v[180:183], v[0:15]
	v_max3_f32 v110, v110, v93, v64
	v_max3_f32 v111, v111, v66, v67
	v_max3_f32 v110, v110, v65, v68
	v_max3_f32 v111, v111, v70, v71
	v_max3_f32 v110, v110, v69, v72
	v_max3_f32 v111, v111, v74, v75
	v_max3_f32 v110, v110, v73, v76
	s_waitcnt lgkmcnt(0)
	v_mfma_f32_32x32x16_bf16 v[16:31], v[224:227], v[180:183], v[16:31]
	v_max3_f32 v111, v111, v78, v79
	v_max3_f32 v110, v110, v77, v111
	v_mov_b32_e32 v111, v110
	s_nop 1
	v_permlane32_swap_b32_e32 v110, v111
	s_waitcnt vmcnt(2)

.LBB0_572:
.LBB0_574:
	ds_read_b128 v[96:99], v199 offset:61440
	s_add_i32 s10, 0, 0x10000
	v_add_u32_e32 v172, s10, v212
	ds_read_b128 v[174:177], v172
	ds_read_b128 v[100:103], v200 offset:61440
	s_add_u32 s4, s92, 0x15668000
	s_addc_u32 s5, s93, 0
	s_mov_b32 m0, s71
	s_nop 0
	global_load_lds_dwordx4 v164, s[4:5]
	s_waitcnt lgkmcnt(2)
	v_mfma_f32_32x32x16_bf16 v[112:127], v[96:99], v[132:135], v[32:47]
	v_add_u32_e32 v220, s10, v214
	ds_read_b128 v[180:183], v220
	ds_read_b128 v[224:227], v201 offset:61440
	s_setprio 1
	v_exp_f32_e32 v80, v80
	v_exp_f32_e32 v189, v81
	v_exp_f32_e32 v188, v82
	v_exp_f32_e32 v81, v83
	s_setprio 0
	s_add_u32 s4, s92, 0x16618280
	s_addc_u32 s5, s93, 0
	s_mov_b32 m0, s90
	s_nop 0
	global_load_lds_dwordx4 v160, s[4:5]
	s_waitcnt lgkmcnt(2)
	v_mfma_f32_32x32x16_bf16 v[112:127], v[100:103], v[128:131], v[112:127]
	v_add_u32_e32 v221, s10, v216
	ds_read_b128 v[228:231], v221
	s_setprio 1
	v_mfma_f32_32x32x16_bf16 v[96:111], v[174:177], v[132:135], v[32:47]
	ds_read_b128 v[232:235], v202 offset:61440
	v_exp_f32_e32 v82, v84
	v_exp_f32_e32 v191, v85
	v_exp_f32_e32 v190, v86
	v_exp_f32_e32 v83, v87
	s_setprio 0
	v_cvt_pk_bf16_f32 v174, v80, v189
	v_cvt_pk_bf16_f32 v175, v188, v81
	v_cvt_pk_bf16_f32 v176, v82, v191
	v_cvt_pk_bf16_f32 v177, v190, v83
	s_and_b64 vcc, exec, s[44:45]
	s_cbranch_vccnz .Lmy_a3_norope
	s_add_u32 s4, s92, 0x32c8500
	s_addc_u32 s5, s93, 0
	s_add_i32 m0, s43, 0x9000
	s_nop 0
	global_load_lds_dwordx4 v162, s[4:5]
.Lmy_a3_norope:
	s_waitcnt lgkmcnt(2)
	v_mfma_f32_32x32x16_bf16 v[112:127], v[224:227], v[144:147], v[112:127]
	v_add_u32_e32 v222, s10, v218
	ds_read_b128 v[236:239], v222
	ds_read_b128 v[224:227], v208 offset:61440
	ds_read_b128 v[240:243], v208 offset:63488
	s_setprio 1
	v_exp_f32_e32 v84, v88
	v_exp_f32_e32 v87, v89
	v_exp_f32_e32 v86, v90
	v_exp_f32_e32 v85, v91
	s_setprio 0
	s_waitcnt lgkmcnt(3)
	v_mfma_f32_32x32x16_bf16 v[112:127], v[232:235], v[140:143], v[112:127]
	s_setprio 1
	v_mfma_f32_32x32x16_bf16 v[96:111], v[180:183], v[128:131], v[96:111]
	v_exp_f32_e32 v88, v92
	v_exp_f32_e32 v91, v93
	v_exp_f32_e32 v90, v94
	v_exp_f32_e32 v89, v95
	v_mfma_f32_32x32x16_bf16 v[96:111], v[228:231], v[144:147], v[96:111]
	ds_read_b128 v[228:231], v207 offset:61440
	ds_read_b128 v[232:235], v207 offset:63488
	s_setprio 0
	v_cvt_pk_bf16_f32 v180, v84, v87
	v_cvt_pk_bf16_f32 v181, v86, v85
	v_cvt_pk_bf16_f32 v182, v88, v91
	v_cvt_pk_bf16_f32 v183, v90, v89
	s_waitcnt lgkmcnt(3)
	v_mfma_f32_32x32x16_bf16 v[112:127], v[224:227], v[148:151], v[112:127]
	s_setprio 1
	v_exp_f32_e32 v64, v64
	v_exp_f32_e32 v93, v65
	v_exp_f32_e32 v92, v66
	v_exp_f32_e32 v65, v67
	s_setprio 0
	s_waitcnt lgkmcnt(1)
	v_mfma_f32_32x32x16_bf16 v[112:127], v[228:231], v[136:139], v[112:127]
	s_setprio 1
	v_mfma_f32_32x32x16_bf16 v[96:111], v[236:239], v[140:143], v[96:111]
	ds_read_b128 v[224:227], v206 offset:49152
	ds_read_b128 v[228:231], v206 offset:53248
	v_exp_f32_e32 v66, v68
	v_exp_f32_e32 v69, v69
	v_exp_f32_e32 v68, v70
	v_exp_f32_e32 v67, v71
	v_mfma_f32_32x32x16_bf16 v[96:111], v[240:243], v[148:151], v[96:111]
	ds_read_b128 v[240:243], v205 offset:49152
	ds_read_b128 v[244:247], v205 offset:53248
	s_setprio 0
	v_cvt_pk_bf16_f32 v236, v64, v93
	v_cvt_pk_bf16_f32 v237, v92, v65
	v_cvt_pk_bf16_f32 v238, v66, v69
	v_cvt_pk_bf16_f32 v239, v68, v67
	s_waitcnt lgkmcnt(3)
	v_mfma_f32_32x32x16_bf16 v[0:15], v[224:227], v[174:177], v[0:15]
	ds_read_b128 v[224:227], v204 offset:49152
	ds_read_b128 v[192:195], v204 offset:53248
	s_setprio 1
	v_exp_f32_e32 v70, v72
	v_exp_f32_e32 v73, v73
	v_exp_f32_e32 v72, v74
	v_exp_f32_e32 v71, v75
	s_setprio 0
	s_waitcnt lgkmcnt(3)
	v_mfma_f32_32x32x16_bf16 v[0:15], v[240:243], v[180:183], v[0:15]
	s_setprio 1
	v_mfma_f32_32x32x16_bf16 v[16:31], v[228:231], v[174:177], v[16:31]
	v_exp_f32_e32 v74, v76
	v_exp_f32_e32 v77, v77
	v_exp_f32_e32 v76, v78
	v_exp_f32_e32 v75, v79
	v_mfma_f32_32x32x16_bf16 v[96:111], v[232:235], v[136:139], v[96:111]
	s_waitcnt lgkmcnt(2)
	v_mfma_f32_32x32x16_bf16 v[16:31], v[244:247], v[180:183], v[16:31]
	ds_read_b128 v[180:183], v203 offset:49152
	ds_read_b128 v[228:231], v203 offset:53248
	s_setprio 0
	v_cvt_pk_bf16_f32 v174, v70, v73
	v_cvt_pk_bf16_f32 v175, v72, v71
	v_cvt_pk_bf16_f32 v176, v74, v77
	v_cvt_pk_bf16_f32 v177, v76, v75
	s_waitcnt lgkmcnt(3)
	v_mfma_f32_32x32x16_bf16 v[0:15], v[224:227], v[236:239], v[0:15]
	v_max_f32_e32 v78, v112, v112
	v_max_f32_e32 v78, 0xf149f2ca, v78
	v_max3_f32 v79, v114, s72, v115
	v_max3_f32 v78, v78, v113, v116
	v_max3_f32 v79, v79, v118, v119
	v_max3_f32 v78, v78, v117, v120
	s_waitcnt lgkmcnt(2)
	v_mfma_f32_32x32x16_bf16 v[16:31], v[192:195], v[236:239], v[16:31]
	v_max3_f32 v79, v79, v122, v123
	v_max3_f32 v78, v78, v121, v124
	v_max3_f32 v79, v79, v126, v127
	s_waitcnt lgkmcnt(1)
	v_mfma_f32_32x32x16_bf16 v[0:15], v[180:183], v[174:177], v[0:15]
	v_max3_f32 v78, v78, v125, v96
	v_max3_f32 v79, v79, v98, v99
	v_max3_f32 v78, v78, v97, v100
	v_max3_f32 v79, v79, v102, v103
	v_max3_f32 v78, v78, v101, v104
	v_max3_f32 v79, v79, v106, v107
	v_max3_f32 v78, v78, v105, v108
	s_waitcnt lgkmcnt(0)
	v_mfma_f32_32x32x16_bf16 v[16:31], v[228:231], v[174:177], v[16:31]
	v_max3_f32 v79, v79, v110, v111
	v_max3_f32 v78, v78, v109, v79
	v_mov_b32_e32 v79, v78
	s_nop 1
	v_permlane32_swap_b32_e32 v78, v79
	s_waitcnt vmcnt(2)

.LBB0_580:
.LBB0_582:
	ds_read_b128 v[64:67], v199
	ds_read_b128 v[174:177], v199 offset:4096
	ds_read_b128 v[68:71], v200
	ds_read_b128 v[180:183], v200 offset:4096
	s_add_u32 s4, s92, 0x15678000
	s_addc_u32 s5, s93, 0
	s_mov_b32 m0, s91
	s_nop 0
	global_load_lds_dwordx4 v164, s[4:5]
	s_waitcnt lgkmcnt(3)
	v_mfma_f32_32x32x16_bf16 v[80:95], v[64:67], v[132:135], v[32:47]
	ds_read_b128 v[188:191], v201
	ds_read_b128 v[192:195], v201 offset:4096
	s_setprio 1
	v_exp_f32_e32 v112, v112
	v_exp_f32_e32 v167, v113
	v_exp_f32_e32 v166, v114
	v_exp_f32_e32 v113, v115
	s_setprio 0
	s_add_u32 s4, s92, 0x16618300
	s_addc_u32 s5, s93, 0
	s_mov_b32 m0, s95
	s_nop 0
	global_load_lds_dwordx4 v160, s[4:5]
	s_waitcnt lgkmcnt(3)
	v_mfma_f32_32x32x16_bf16 v[80:95], v[68:71], v[128:131], v[80:95]
	s_setprio 1
	v_mfma_f32_32x32x16_bf16 v[64:79], v[174:177], v[132:135], v[32:47]
	ds_read_b128 v[224:227], v202
	ds_read_b128 v[228:231], v202 offset:4096
	v_exp_f32_e32 v114, v116
	v_exp_f32_e32 v169, v117
	v_exp_f32_e32 v168, v118
	v_exp_f32_e32 v115, v119
	s_setprio 0
	v_cvt_pk_bf16_f32 v174, v112, v167
	v_cvt_pk_bf16_f32 v175, v166, v113
	v_cvt_pk_bf16_f32 v176, v114, v169
	v_cvt_pk_bf16_f32 v177, v168, v115
	s_and_b64 vcc, exec, s[44:45]
	s_cbranch_vccnz .Lmy_a4_norope
	s_add_u32 s4, s92, 0x33b8500
	s_addc_u32 s5, s93, 0
	s_add_i32 m0, s43, 0xe000
	s_nop 0
	global_load_lds_dwordx4 v162, s[4:5]
.Lmy_a4_norope:
	s_waitcnt lgkmcnt(3)
	v_mfma_f32_32x32x16_bf16 v[80:95], v[188:191], v[144:147], v[80:95]
	ds_read_b128 v[188:191], v210 offset:16384
	ds_read_b128 v[232:235], v210 offset:18432
	s_setprio 1
	v_exp_f32_e32 v116, v120
	v_exp_f32_e32 v121, v121
	v_exp_f32_e32 v120, v122
	v_exp_f32_e32 v117, v123
	s_setprio 0
	s_waitcnt lgkmcnt(3)
	v_mfma_f32_32x32x16_bf16 v[80:95], v[224:227], v[140:143], v[80:95]
	s_setprio 1
	v_mfma_f32_32x32x16_bf16 v[64:79], v[180:183], v[128:131], v[64:79]
	v_exp_f32_e32 v118, v124
	v_exp_f32_e32 v123, v125
	v_exp_f32_e32 v122, v126
	v_exp_f32_e32 v119, v127
	v_mfma_f32_32x32x16_bf16 v[64:79], v[192:195], v[144:147], v[64:79]
	ds_read_b128 v[192:195], v211 offset:16384
	ds_read_b128 v[224:227], v211 offset:18432
	s_setprio 0
	v_cvt_pk_bf16_f32 v180, v116, v121
	v_cvt_pk_bf16_f32 v181, v120, v117
	v_cvt_pk_bf16_f32 v182, v118, v123
	v_cvt_pk_bf16_f32 v183, v122, v119
	s_waitcnt lgkmcnt(3)
	v_mfma_f32_32x32x16_bf16 v[80:95], v[188:191], v[148:151], v[80:95]
	s_setprio 1
	v_exp_f32_e32 v96, v96
	v_exp_f32_e32 v125, v97
	v_exp_f32_e32 v124, v98
	v_exp_f32_e32 v97, v99
	s_setprio 0
	s_waitcnt lgkmcnt(1)
	v_mfma_f32_32x32x16_bf16 v[80:95], v[192:195], v[136:139], v[80:95]
	s_setprio 1
	v_mfma_f32_32x32x16_bf16 v[64:79], v[228:231], v[140:143], v[64:79]
	v_exp_f32_e32 v98, v100
	v_exp_f32_e32 v101, v101
	v_exp_f32_e32 v100, v102
	v_exp_f32_e32 v99, v103
	v_mfma_f32_32x32x16_bf16 v[64:79], v[232:235], v[148:151], v[64:79]
	s_setprio 0
	v_add_u32_e32 v170, 0, v213
	ds_read_b128 v[190:193], v170 offset:61440
	v_add_u32_e32 v171, s10, v213
	ds_read_b128 v[228:231], v171
	v_cvt_pk_bf16_f32 v232, v96, v125
	v_cvt_pk_bf16_f32 v233, v124, v97
	v_cvt_pk_bf16_f32 v234, v98, v101
	v_cvt_pk_bf16_f32 v235, v100, v99
	s_waitcnt lgkmcnt(1)
	v_mfma_f32_32x32x16_bf16 v[0:15], v[190:193], v[174:177], v[0:15]
	v_add_u32_e32 v188, 0, v215
	ds_read_b128 v[236:239], v188 offset:61440
	v_add_u32_e32 v189, s10, v215
	ds_read_b128 v[240:243], v189
	s_setprio 1
	v_exp_f32_e32 v102, v104
	v_exp_f32_e32 v105, v105
	v_exp_f32_e32 v104, v106
	v_exp_f32_e32 v103, v107
	s_setprio 0
	s_waitcnt lgkmcnt(1)
	v_mfma_f32_32x32x16_bf16 v[0:15], v[236:239], v[180:183], v[0:15]
	v_add_u32_e32 v190, 0, v217
	ds_read_b128 v[192:195], v190 offset:61440
	v_add_u32_e32 v191, s10, v217
	ds_read_b128 v[244:247], v191
	s_setprio 1
	v_mfma_f32_32x32x16_bf16 v[16:31], v[228:231], v[174:177], v[16:31]
	v_exp_f32_e32 v106, v108
	v_exp_f32_e32 v109, v109
	v_exp_f32_e32 v108, v110
	v_exp_f32_e32 v107, v111
	v_mfma_f32_32x32x16_bf16 v[64:79], v[224:227], v[136:139], v[64:79]
	s_waitcnt lgkmcnt(2)
	v_mfma_f32_32x32x16_bf16 v[16:31], v[240:243], v[180:183], v[16:31]
	s_setprio 0
	v_cvt_pk_bf16_f32 v174, v102, v105
	v_cvt_pk_bf16_f32 v175, v104, v103
	v_cvt_pk_bf16_f32 v176, v106, v109
	v_cvt_pk_bf16_f32 v177, v108, v107
	s_waitcnt lgkmcnt(1)
	v_mfma_f32_32x32x16_bf16 v[0:15], v[192:195], v[232:235], v[0:15]
	v_add_u32_e32 v126, 0, v219
	ds_read_b128 v[180:183], v126 offset:61440
	v_add_u32_e32 v127, s10, v219
	ds_read_b128 v[224:227], v127
	v_max_f32_e32 v110, v80, v80
	v_max_f32_e32 v110, 0xf149f2ca, v110
	v_max3_f32 v111, v82, s72, v83
	s_waitcnt lgkmcnt(2)
	v_mfma_f32_32x32x16_bf16 v[16:31], v[244:247], v[232:235], v[16:31]
	v_max3_f32 v110, v110, v81, v84
	v_max3_f32 v111, v111, v86, v87
	v_max3_f32 v110, v110, v85, v88
	v_max3_f32 v111, v111, v90, v91
	v_max3_f32 v110, v110, v89, v92
	v_max3_f32 v111, v111, v94, v95
	s_waitcnt lgkmcnt(1)
	v_mfma_f32_32x32x16_bf16 v[0:15], v[180:183], v[174:177], v[0:15]
	v_max3_f32 v110, v110, v93, v64
	v_max3_f32 v111, v111, v66, v67
	v_max3_f32 v110, v110, v65, v68
	v_max3_f32 v111, v111, v70, v71
	v_max3_f32 v110, v110, v69, v72
	v_max3_f32 v111, v111, v74, v75
	v_max3_f32 v110, v110, v73, v76
	s_waitcnt lgkmcnt(0)
	v_mfma_f32_32x32x16_bf16 v[16:31], v[224:227], v[174:177], v[16:31]
	v_max3_f32 v111, v111, v78, v79
	v_max3_f32 v110, v110, v77, v111
	v_mov_b32_e32 v111, v110
	s_nop 1
	v_permlane32_swap_b32_e32 v110, v111
	s_waitcnt vmcnt(2)
